# barriers as before plus: XCC-id table at start, co-location check at barrier 1, leaders skip the L2 write-back at seams 3-5 when every row block's four workgroups share an XCD
# baseline (speedup 1.0000x reference)
; #define LAS __attribute__((address_space(3)))
; __device__ __forceinline__ unsigned xb_add(unsigned* p, unsigned v) { return __hip_atomic_fetch_add(p, v, __ATOMIC_RELAXED, __HIP_MEMORY_SCOPE_AGENT); }
; __device__ __forceinline__ unsigned xb_xcc_id() { return (unsigned)__builtin_amdgcn_s_getreg((3 << 11) | 20) & 0xFu; }
; __device__ __forceinline__ XcdBarrier xcd_barrier_post(unsigned* bar, volatile LAS unsigned* st) {
;     XcdBarrier b; b.bar = bar; b.x = xb_xcc_id(); b.st = st;
;     if (threadIdx.x == 0) (void)xb_add(&bar[XB_XCNT(b.x)], 1u);
;     return b;
; __global__ void __launch_bounds__(NTHREADS, 2) hybrid_fwd(Args args) {
;     ...
;     const int tid = threadIdx.x, lane = tid & 63, wave = __builtin_amdgcn_readfirstlane(tid >> 6);
;     const int G = gridDim.x;
;     unsigned char* ws = args.ws;
;     const int lo = args.ph_lo, hi = args.ph_hi;
;     volatile LAS unsigned* MISC = (volatile LAS unsigned*)(lds + MISC_OFF);
;     if (tid < 2) MISC[tid] = 0u;
;     __syncthreads();
;     const XcdBarrier bar = xcd_barrier_post((unsigned*)ws, MISC);
_Z10hybrid_fwd4Args:
	s_load_dwordx8 s[68:75], s[0:1], 0x60
	s_load_dwordx8 s[4:11], s[0:1], 0x40
	s_load_dword s3, s[0:1], 0x88
	s_load_dwordx2 s[84:85], s[0:1], 0x80
	s_mov_b32 s33, s2
	s_add_u32 s2, s0, 0x80
	s_waitcnt lgkmcnt(0)
	v_writelane_b32 v254, s4, 0
	v_and_b32_e32 v188, 0x3ff, v0
	v_cmp_gt_u32_e32 vcc, 3, v188
	v_writelane_b32 v254, s5, 1
	v_writelane_b32 v254, s6, 2
	v_writelane_b32 v254, s7, 3
	v_writelane_b32 v254, s8, 4
	v_writelane_b32 v254, s9, 5
	v_writelane_b32 v254, s10, 6
	v_writelane_b32 v254, s11, 7
	v_writelane_b32 v254, s3, 8
	s_addc_u32 s3, s1, 0
	v_readfirstlane_b32 s8, v188
	s_and_saveexec_b64 s[4:5], vcc
	v_lshl_add_u32 v1, v188, 2, 0
	v_add_u32_e32 v1, 0x26700, v1
	v_mov_b32_e32 v2, 0
	ds_write_b32 v1, v2
	s_or_b64 exec, exec, s[4:5]
	s_waitcnt lgkmcnt(0)
	s_barrier
	s_getreg_b32 s4, hwreg(HW_REG_XCC_ID, 0, 4)
	s_and_b32 s88, s4, 15
	v_cmp_eq_u32_e64 s[6:7], 0, v188
	s_mov_b64 s[4:5], exec
	s_nop 0
	v_writelane_b32 v254, s6, 9
	s_nop 1
	v_writelane_b32 v254, s7, 10
	s_and_b64 s[6:7], s[4:5], s[6:7]
	s_mov_b64 exec, s[6:7]
	s_cbranch_execz .LBB0_5
	s_mov_b64 s[6:7], exec
	v_mbcnt_lo_u32_b32 v1, s6, 0
	v_mbcnt_hi_u32_b32 v1, s7, v1
	v_cmp_eq_u32_e32 vcc, 0, v1
	s_and_b64 s[10:11], exec, vcc
	s_mov_b64 exec, s[10:11]
	s_cbranch_execz .LBB0_5
	s_lshl_b32 s9, s88, 8
	s_bcnt1_i32_b64 s6, s[6:7]
	v_mov_b32_e32 v1, s9
	v_mov_b32_e32 v2, s6
	global_atomic_add v1, v2, s[72:73] offset:1024
	s_lshl_b32 s9, s33, 2
	s_addk_i32 s9, 0x3800
	s_add_i32 s6, s88, 1
	v_mov_b32_e32 v1, s9
	v_mov_b32_e32 v2, s6
	global_atomic_add v1, v2, s[72:73]

; __device__ __forceinline__ unsigned xb_ld(unsigned* p)              { return __hip_atomic_load(p, __ATOMIC_RELAXED, __HIP_MEMORY_SCOPE_AGENT); }
; __device__ __forceinline__ unsigned xb_add(unsigned* p, unsigned v) { return __hip_atomic_fetch_add(p, v, __ATOMIC_RELAXED, __HIP_MEMORY_SCOPE_AGENT); }
; #define XB_SPIN(cond, bar) do { unsigned _sp = 0; while (cond) { __builtin_amdgcn_s_sleep(1); \
;     if ((++_sp & 255u) == 0u) { if (xb_ld(&(bar)[XB_TMO])) break; if (_sp > XB_SPIN_CAP) { atomicAdd(&(bar)[XB_TMO], 1u); break; } } } } while (0)
; __device__ __forceinline__ void xcd_barrier(const XcdBarrier& b) {
;     asm volatile("s_waitcnt vmcnt(0)" ::: "memory");
;     __syncthreads();
;     if (threadIdx.x == 0) {
;         unsigned* bar = b.bar;
;         __builtin_amdgcn_s_waitcnt(0);
;         unsigned nloc = b.st[0], nx = b.st[1];
;         if (nloc == 0u) { xcd_barrier_complete(bar, b.x, nloc, nx); b.st[0] = nloc; b.st[1] = nx; }
;         const unsigned old = xb_add(&bar[XB_XSUB(b.x)], 1u);
;         const unsigned gen = old / nloc;
;         if (old + 1u == (gen + 1u) * nloc) {
;             __builtin_amdgcn_fence(__ATOMIC_RELEASE, "agent");
;             asm volatile("s_waitcnt vmcnt(0)" ::: "memory");
;             const unsigned og = xb_add(&bar[XB_TOP], 1u);
;             const unsigned tg = og / nx;
;             if (og + 1u == (tg + 1u) * nx) xb_add(&bar[XB_TOPGEN], 1u);
;             else XB_SPIN(xb_ld(&bar[XB_TOPGEN]) == tg, bar);
;             __builtin_amdgcn_fence(__ATOMIC_ACQUIRE, "agent");
;             xb_add(&bar[XB_XGEN(b.x)], 1u);
;             asm volatile("s_waitcnt vmcnt(0)" ::: "memory");
;         } else {
;             XB_SPIN(xb_ld(&bar[XB_XGEN(b.x)]) == gen, bar);
;             __builtin_amdgcn_fence(__ATOMIC_ACQUIRE, "agent");
;             asm volatile("s_waitcnt vmcnt(0)" ::: "memory");
;         }
.LBB0_157:
	s_cmp_gt_i32 s75, 2
	s_cselect_b64 s[0:1], -1, 0
	s_and_b64 s[2:3], s[4:5], s[0:1]
	s_andn2_b64 vcc, exec, s[2:3]
	s_cbranch_vccnz .LBB0_211
	s_waitcnt vmcnt(0)
	s_waitcnt vmcnt(0) lgkmcnt(0)
	s_barrier
	s_mov_b64 s[2:3], exec
	v_readlane_b32 s4, v254, 9
	v_readlane_b32 s5, v254, 10
	s_and_b64 s[4:5], s[2:3], s[4:5]
	s_mov_b64 exec, s[4:5]
	s_cbranch_execz .LBB0_210
	s_cmp_eq_u32 s74, 1
	s_cbranch_scc1 .Lmy_fb_1_orig
	s_mov_b64 s[10:11], exec
	s_mov_b64 exec, -1
	v_mbcnt_lo_u32_b32 v7, -1, 0
	v_mbcnt_hi_u32_b32 v7, -1, v7
	v_lshlrev_b32_e32 v7, 2, v7
	v_add_u32_e32 v7, 0x3800, v7
	global_load_dword v8, v7, s[72:73] sc1
	global_load_dword v9, v7, s[72:73] offset:256 sc1
	global_load_dword v10, v7, s[72:73] offset:512 sc1
	global_load_dword v11, v7, s[72:73] offset:768 sc1
	s_waitcnt vmcnt(0)
	v_cmp_ne_u32_e32 vcc, 0, v8
	v_cmp_eq_u32_e64 s[12:13], v8, v9
	v_cmp_eq_u32_e64 s[14:15], v8, v10
	v_cmp_eq_u32_e64 s[16:17], v8, v11
	s_and_b64 vcc, vcc, s[12:13]
	s_and_b64 s[14:15], s[14:15], s[16:17]
	s_and_b64 vcc, vcc, s[14:15]
	s_cmp_eq_u64 vcc, exec
	s_cselect_b32 s12, 1, 0
	s_cmpk_eq_i32 s84, 0x100
	s_cselect_b32 s12, s12, 0
	s_mov_b64 exec, s[10:11]
	v_mov_b32_e32 v7, s12
	v_mov_b32_e32 v0, 0x26708
	ds_write_b32 v0, v7
	s_add_i32 s4, 0, 0x26700
	v_mov_b32_e32 v0, s4
	ds_read2_b32 v[2:3], v0 offset1:1
	s_lshl_b32 s4, s88, 8
	s_add_u32 s4, s72, s4
	s_addc_u32 s5, s73, 0
	v_mov_b32_e32 v4, 0x1000
	v_mov_b32_e32 v5, 1
	global_atomic_add v4, v4, v5, s[4:5] offset:1024 sc0
	s_sub_i32 s6, 2, s74
	s_waitcnt lgkmcnt(0)
	v_readfirstlane_b32 s7, v2
	v_readfirstlane_b32 s8, v3
	s_mul_i32 s7, s7, s6
	s_add_i32 s6, s6, -1
	s_mul_i32 s8, s8, s6
	s_add_i32 s8, s8, 1
	v_mov_b32_e32 v6, 0x2000
	s_waitcnt vmcnt(0)
	v_readfirstlane_b32 s10, v4
	s_add_i32 s10, s10, 1
	s_cmp_lg_u32 s10, s7
	s_cbranch_scc1 .Lmy_fb_1_wait
	buffer_wbl2 sc1
	s_mov_b64 s[10:11], exec
	s_mov_b64 exec, 0xffff
	v_mbcnt_lo_u32_b32 v7, -1, 0
	v_lshlrev_b32_e32 v7, 8, v7
	v_add_u32_e32 v7, 0x2400, v7
	v_mov_b32_e32 v8, 1
	s_waitcnt vmcnt(0)
	global_atomic_add v7, v8, s[72:73]
	s_mov_b64 exec, s[10:11]

; __device__ __forceinline__ unsigned xb_ld(unsigned* p)              { return __hip_atomic_load(p, __ATOMIC_RELAXED, __HIP_MEMORY_SCOPE_AGENT); }
; __device__ __forceinline__ unsigned xb_add(unsigned* p, unsigned v) { return __hip_atomic_fetch_add(p, v, __ATOMIC_RELAXED, __HIP_MEMORY_SCOPE_AGENT); }
; #define XB_SPIN(cond, bar) do { unsigned _sp = 0; while (cond) { __builtin_amdgcn_s_sleep(1); \
;     if ((++_sp & 255u) == 0u) { if (xb_ld(&(bar)[XB_TMO])) break; if (_sp > XB_SPIN_CAP) { atomicAdd(&(bar)[XB_TMO], 1u); break; } } } } while (0)
; __device__ __forceinline__ void xcd_barrier(const XcdBarrier& b) {
;     asm volatile("s_waitcnt vmcnt(0)" ::: "memory");
;     __syncthreads();
;     if (threadIdx.x == 0) {
;         unsigned* bar = b.bar;
;         __builtin_amdgcn_s_waitcnt(0);
;         unsigned nloc = b.st[0], nx = b.st[1];
;         if (nloc == 0u) { xcd_barrier_complete(bar, b.x, nloc, nx); b.st[0] = nloc; b.st[1] = nx; }
;         const unsigned old = xb_add(&bar[XB_XSUB(b.x)], 1u);
;         const unsigned gen = old / nloc;
;         if (old + 1u == (gen + 1u) * nloc) {
;             __builtin_amdgcn_fence(__ATOMIC_RELEASE, "agent");
;             asm volatile("s_waitcnt vmcnt(0)" ::: "memory");
;             const unsigned og = xb_add(&bar[XB_TOP], 1u);
;             const unsigned tg = og / nx;
;             if (og + 1u == (tg + 1u) * nx) xb_add(&bar[XB_TOPGEN], 1u);
;             else XB_SPIN(xb_ld(&bar[XB_TOPGEN]) == tg, bar);
;             __builtin_amdgcn_fence(__ATOMIC_ACQUIRE, "agent");
;             xb_add(&bar[XB_XGEN(b.x)], 1u);
;             asm volatile("s_waitcnt vmcnt(0)" ::: "memory");
;         } else {
;             XB_SPIN(xb_ld(&bar[XB_XGEN(b.x)]) == gen, bar);
;             __builtin_amdgcn_fence(__ATOMIC_ACQUIRE, "agent");
;             asm volatile("s_waitcnt vmcnt(0)" ::: "memory");
;         }
.LBB0_808:
	s_cmp_gt_i32 s75, 4
	s_cselect_b64 s[2:3], -1, 0
	s_and_b64 s[0:1], s[0:1], s[2:3]
	s_andn2_b64 vcc, exec, s[0:1]
	s_cbranch_vccnz .LBB0_862
	s_waitcnt vmcnt(0)
	s_waitcnt vmcnt(0) lgkmcnt(0)
	s_barrier
	s_mov_b64 s[0:1], exec
	v_readlane_b32 s4, v254, 9
	v_readlane_b32 s5, v254, 10
	s_and_b64 s[4:5], s[0:1], s[4:5]
	s_mov_b64 exec, s[4:5]
	s_cbranch_execz .LBB0_861
	s_cmp_eq_u32 s74, 3
	s_cbranch_scc1 .Lmy_fb_3_orig
	s_add_i32 s4, 0, 0x26700
	v_mov_b32_e32 v0, s4
	ds_read2_b32 v[2:3], v0 offset1:1
	ds_read_b32 v9, v0 offset:8
	s_lshl_b32 s4, s88, 8
	s_add_u32 s4, s72, s4
	s_addc_u32 s5, s73, 0
	v_mov_b32_e32 v4, 0x1000
	v_mov_b32_e32 v5, 1
	global_atomic_add v4, v4, v5, s[4:5] offset:1024 sc0
	s_sub_i32 s6, 4, s74
	s_waitcnt lgkmcnt(0)
	v_readfirstlane_b32 s7, v2
	v_readfirstlane_b32 s8, v3
	v_readfirstlane_b32 s9, v9
	s_mul_i32 s7, s7, s6
	s_add_i32 s6, s6, -1
	s_mul_i32 s8, s8, s6
	s_add_i32 s8, s8, 1
	v_mov_b32_e32 v6, 0x2000
	s_waitcnt vmcnt(0)
	v_readfirstlane_b32 s10, v4
	s_add_i32 s10, s10, 1
	s_cmp_lg_u32 s10, s7
	s_cbranch_scc1 .Lmy_fb_3_wait
	s_cmp_lg_u32 s9, 0
	s_cbranch_scc1 .Lmy_fb_3_nowb
	buffer_wbl2 sc1
.Lmy_fb_3_nowb:
	s_mov_b64 s[10:11], exec
	s_mov_b64 exec, 0xffff
	v_mbcnt_lo_u32_b32 v7, -1, 0
	v_lshlrev_b32_e32 v7, 8, v7
	v_add_u32_e32 v7, 0x2400, v7
	v_mov_b32_e32 v8, 1
	s_waitcnt vmcnt(0)
	global_atomic_add v7, v8, s[72:73]
	s_mov_b64 exec, s[10:11]

; __device__ __forceinline__ unsigned xb_ld(unsigned* p)              { return __hip_atomic_load(p, __ATOMIC_RELAXED, __HIP_MEMORY_SCOPE_AGENT); }
; __device__ __forceinline__ unsigned xb_add(unsigned* p, unsigned v) { return __hip_atomic_fetch_add(p, v, __ATOMIC_RELAXED, __HIP_MEMORY_SCOPE_AGENT); }
; #define XB_SPIN(cond, bar) do { unsigned _sp = 0; while (cond) { __builtin_amdgcn_s_sleep(1); \
;     if ((++_sp & 255u) == 0u) { if (xb_ld(&(bar)[XB_TMO])) break; if (_sp > XB_SPIN_CAP) { atomicAdd(&(bar)[XB_TMO], 1u); break; } } } } while (0)
; __device__ __forceinline__ void xcd_barrier(const XcdBarrier& b) {
;     asm volatile("s_waitcnt vmcnt(0)" ::: "memory");
;     __syncthreads();
;     if (threadIdx.x == 0) {
;         unsigned* bar = b.bar;
;         __builtin_amdgcn_s_waitcnt(0);
;         unsigned nloc = b.st[0], nx = b.st[1];
;         if (nloc == 0u) { xcd_barrier_complete(bar, b.x, nloc, nx); b.st[0] = nloc; b.st[1] = nx; }
;         const unsigned old = xb_add(&bar[XB_XSUB(b.x)], 1u);
;         const unsigned gen = old / nloc;
;         if (old + 1u == (gen + 1u) * nloc) {
;             __builtin_amdgcn_fence(__ATOMIC_RELEASE, "agent");
;             asm volatile("s_waitcnt vmcnt(0)" ::: "memory");
;             const unsigned og = xb_add(&bar[XB_TOP], 1u);
;             const unsigned tg = og / nx;
;             if (og + 1u == (tg + 1u) * nx) xb_add(&bar[XB_TOPGEN], 1u);
;             else XB_SPIN(xb_ld(&bar[XB_TOPGEN]) == tg, bar);
;             __builtin_amdgcn_fence(__ATOMIC_ACQUIRE, "agent");
;             xb_add(&bar[XB_XGEN(b.x)], 1u);
;             asm volatile("s_waitcnt vmcnt(0)" ::: "memory");
;         } else {
;             XB_SPIN(xb_ld(&bar[XB_XGEN(b.x)]) == gen, bar);
;             __builtin_amdgcn_fence(__ATOMIC_ACQUIRE, "agent");
;             asm volatile("s_waitcnt vmcnt(0)" ::: "memory");
;         }
.LBB0_905:
	s_cmp_gt_i32 s75, 5
	s_cselect_b64 s[2:3], -1, 0
	s_and_b64 s[0:1], s[0:1], s[2:3]
	s_andn2_b64 vcc, exec, s[0:1]
	s_cbranch_vccnz .LBB0_959
	s_waitcnt vmcnt(0)
	s_waitcnt vmcnt(0) lgkmcnt(0)
	s_barrier
	s_mov_b64 s[0:1], exec
	v_readlane_b32 s4, v254, 9
	v_readlane_b32 s5, v254, 10
	s_and_b64 s[4:5], s[0:1], s[4:5]
	s_mov_b64 exec, s[4:5]
	s_cbranch_execz .LBB0_958
	s_cmp_eq_u32 s74, 4
	s_cbranch_scc1 .Lmy_fb_4_orig
	s_add_i32 s4, 0, 0x26700
	v_mov_b32_e32 v0, s4
	ds_read2_b32 v[2:3], v0 offset1:1
	ds_read_b32 v9, v0 offset:8
	s_lshl_b32 s4, s88, 8
	s_add_u32 s4, s72, s4
	s_addc_u32 s5, s73, 0
	v_mov_b32_e32 v4, 0x1000
	v_mov_b32_e32 v5, 1
	global_atomic_add v4, v4, v5, s[4:5] offset:1024 sc0
	s_sub_i32 s6, 5, s74
	s_waitcnt lgkmcnt(0)
	v_readfirstlane_b32 s7, v2
	v_readfirstlane_b32 s8, v3
	v_readfirstlane_b32 s9, v9
	s_mul_i32 s7, s7, s6
	s_add_i32 s6, s6, -1
	s_mul_i32 s8, s8, s6
	s_add_i32 s8, s8, 1
	v_mov_b32_e32 v6, 0x2000
	s_waitcnt vmcnt(0)
	v_readfirstlane_b32 s10, v4
	s_add_i32 s10, s10, 1
	s_cmp_lg_u32 s10, s7
	s_cbranch_scc1 .Lmy_fb_4_wait
	s_cmp_lg_u32 s9, 0
	s_cbranch_scc1 .Lmy_fb_4_nowb
	buffer_wbl2 sc1

; __device__ __forceinline__ unsigned xb_ld(unsigned* p)              { return __hip_atomic_load(p, __ATOMIC_RELAXED, __HIP_MEMORY_SCOPE_AGENT); }
; __device__ __forceinline__ unsigned xb_add(unsigned* p, unsigned v) { return __hip_atomic_fetch_add(p, v, __ATOMIC_RELAXED, __HIP_MEMORY_SCOPE_AGENT); }
; #define XB_SPIN(cond, bar) do { unsigned _sp = 0; while (cond) { __builtin_amdgcn_s_sleep(1); \
;     if ((++_sp & 255u) == 0u) { if (xb_ld(&(bar)[XB_TMO])) break; if (_sp > XB_SPIN_CAP) { atomicAdd(&(bar)[XB_TMO], 1u); break; } } } } while (0)
; __device__ __forceinline__ void xcd_barrier(const XcdBarrier& b) {
;     asm volatile("s_waitcnt vmcnt(0)" ::: "memory");
;     __syncthreads();
;     if (threadIdx.x == 0) {
;         unsigned* bar = b.bar;
;         __builtin_amdgcn_s_waitcnt(0);
;         unsigned nloc = b.st[0], nx = b.st[1];
;         if (nloc == 0u) { xcd_barrier_complete(bar, b.x, nloc, nx); b.st[0] = nloc; b.st[1] = nx; }
;         const unsigned old = xb_add(&bar[XB_XSUB(b.x)], 1u);
;         const unsigned gen = old / nloc;
;         if (old + 1u == (gen + 1u) * nloc) {
;             __builtin_amdgcn_fence(__ATOMIC_RELEASE, "agent");
;             asm volatile("s_waitcnt vmcnt(0)" ::: "memory");
;             const unsigned og = xb_add(&bar[XB_TOP], 1u);
;             const unsigned tg = og / nx;
;             if (og + 1u == (tg + 1u) * nx) xb_add(&bar[XB_TOPGEN], 1u);
;             else XB_SPIN(xb_ld(&bar[XB_TOPGEN]) == tg, bar);
;             __builtin_amdgcn_fence(__ATOMIC_ACQUIRE, "agent");
;             xb_add(&bar[XB_XGEN(b.x)], 1u);
;             asm volatile("s_waitcnt vmcnt(0)" ::: "memory");
;         } else {
;             XB_SPIN(xb_ld(&bar[XB_XGEN(b.x)]) == gen, bar);
;             __builtin_amdgcn_fence(__ATOMIC_ACQUIRE, "agent");
;             asm volatile("s_waitcnt vmcnt(0)" ::: "memory");
;         }
.LBB0_976:
	s_cmp_gt_i32 s75, 6
	s_cselect_b64 s[2:3], -1, 0
	s_and_b64 s[0:1], s[0:1], s[2:3]
	s_andn2_b64 vcc, exec, s[0:1]
	s_cbranch_vccnz .LBB0_1030
	s_waitcnt vmcnt(0)
	s_waitcnt vmcnt(0) lgkmcnt(0)
	s_barrier
	s_mov_b64 s[0:1], exec
	v_readlane_b32 s4, v254, 9
	v_readlane_b32 s5, v254, 10
	s_and_b64 s[4:5], s[0:1], s[4:5]
	s_mov_b64 exec, s[4:5]
	s_cbranch_execz .LBB0_1029
	s_cmp_eq_u32 s74, 5
	s_cbranch_scc1 .Lmy_fb_5_orig
	s_add_i32 s4, 0, 0x26700
	v_mov_b32_e32 v0, s4
	ds_read2_b32 v[2:3], v0 offset1:1
	ds_read_b32 v9, v0 offset:8
	s_lshl_b32 s4, s88, 8
	s_add_u32 s4, s72, s4
	s_addc_u32 s5, s73, 0
	v_mov_b32_e32 v4, 0x1000
	v_mov_b32_e32 v5, 1
	global_atomic_add v4, v4, v5, s[4:5] offset:1024 sc0
	s_sub_i32 s6, 6, s74
	s_waitcnt lgkmcnt(0)
	v_readfirstlane_b32 s7, v2
	v_readfirstlane_b32 s8, v3
	v_readfirstlane_b32 s9, v9
	s_mul_i32 s7, s7, s6
	s_add_i32 s6, s6, -1
	s_mul_i32 s8, s8, s6
	s_add_i32 s8, s8, 1
	v_mov_b32_e32 v6, 0x2000
	s_waitcnt vmcnt(0)
	v_readfirstlane_b32 s10, v4
	s_add_i32 s10, s10, 1
	s_cmp_lg_u32 s10, s7
	s_cbranch_scc1 .Lmy_fb_5_wait
	s_cmp_lg_u32 s9, 0
	s_cbranch_scc1 .Lmy_fb_5_nowb
	buffer_wbl2 sc1
